# code placement: the three K-loop heads padded (outside the loops) to byte phase 0 mod 64
# speedup vs baseline: 1.0036x; 1.0036x over previous
;     ...
;         const bool has_next = S.next(ui + 1, nxt);
;         const char* nA = has_next ? nxt.A : cA; const char* nB = has_next ? nxt.B : cB;
;         for (int t = 0; t < nt; t += 2) {
;             const bool last = (t == nt - 2);
;             const char* a1 = cA + (size_t)(t + 1) * kstep;
;             const char* a2 = last ? nA : cA + (size_t)(t + 2) * kstep; const char* b2 = last ? nB : cB + (size_t)(t + 2) * kstep;
.LBB0_158:
	s_mov_b64 s[56:57], s[18:19]
	s_mov_b64 s[16:17], s[2:3]
	v_mov_b32_e32 v228, v128
	s_xor_b64 s[2:3], s[36:37], -1
	v_mov_b32_e32 v128, s57
	s_and_b64 s[0:1], s[36:37], exec
	v_cndmask_b32_e64 v132, v189, v128, s[36:37]
	v_mov_b32_e32 v128, s56
	s_mov_b64 s[68:69], s[8:9]
	s_mov_b64 s[54:55], s[40:41]
	s_cselect_b32 s18, s17, s13
	s_cselect_b32 s19, s16, s12
	v_cndmask_b32_e64 v133, v188, v128, s[36:37]
	s_mov_b32 s8, 0
	s_mov_b64 s[0:1], 0x100
	v_mov_b64_e32 v[128:129], v[202:203]
	v_mov_b64_e32 v[130:131], v[200:201]
	s_nop 0
	s_nop 0
	s_nop 0
	s_nop 0
	s_nop 0
	s_nop 0
	s_nop 0

;     ...
;         const bool has_next = S.next(ui + 1, nxt);
;         const char* nA = has_next ? nxt.A : cA; const char* nB = has_next ? nxt.B : cB;
;         for (int t = 0; t < nt; t += 2) {
;             const bool last = (t == nt - 2);
;             const char* a1 = cA + (size_t)(t + 1) * kstep;
;             const char* a2 = last ? nA : cA + (size_t)(t + 2) * kstep; const char* b2 = last ? nB : cB + (size_t)(t + 2) * kstep;
.LBB0_317:
	s_mov_b64 s[54:55], s[68:69]
	v_mov_b32_e32 v189, v128
	s_xor_b64 s[66:67], s[64:65], -1
	v_mov_b32_e32 v128, s55
	s_mov_b64 s[36:37], s[38:39]
	s_and_b64 s[0:1], s[64:65], exec
	v_cndmask_b32_e64 v132, v161, v128, s[64:65]
	v_mov_b32_e32 v128, s54
	s_mov_b64 s[6:7], s[56:57]
	s_mov_b64 s[14:15], s[58:59]
	s_mov_b32 s26, s19
	s_cselect_b32 s13, s37, s3
	s_cselect_b32 s56, s36, s2
	v_cndmask_b32_e64 v133, v160, v128, s[64:65]
	s_mov_b32 s38, 0
	s_mov_b64 s[0:1], 0x100
	v_mov_b64_e32 v[128:129], v[172:173]
	v_mov_b64_e32 v[130:131], v[170:171]
	s_nop 0
	s_nop 0
	s_nop 0
	s_nop 0
	s_nop 0

;     ...
;         const bool has_next = S.next(ui + 1, nxt);
;         const char* nA = has_next ? nxt.A : cA; const char* nB = has_next ? nxt.B : cB;
;         for (int t = 0; t < nt; t += 2) {
;             const bool last = (t == nt - 2);
;             const char* a1 = cA + (size_t)(t + 1) * kstep;
;             const char* a2 = last ? nA : cA + (size_t)(t + 2) * kstep; const char* b2 = last ? nB : cB + (size_t)(t + 2) * kstep;
.LBB0_415:
	s_mov_b64 s[12:13], s[18:19]
	v_mov_b32_e32 v150, v144
	s_xor_b64 s[18:19], s[16:17], -1
	v_mov_b32_e32 v144, s13
	s_mov_b64 s[68:69], s[2:3]
	s_and_b64 s[0:1], s[16:17], exec
	v_cndmask_b32_e64 v151, v129, v144, s[16:17]
	v_mov_b32_e32 v144, s12
	s_mov_b64 s[56:57], s[8:9]
	s_mov_b32 s62, s26
	s_cselect_b32 s6, s69, s53
	s_cselect_b32 s7, s68, s52
	v_cndmask_b32_e64 v152, v128, v144, s[16:17]
	s_mov_b32 s2, 0
	s_mov_b64 s[0:1], 0x100
	v_mov_b64_e32 v[144:145], v[142:143]
	v_mov_b64_e32 v[146:147], v[140:141]
	s_nop 0
